# A/B: static s_setprio 1 on the OLDER wave half (0-3) instead of the younger, flips deleted
# baseline (speedup 1.0000x reference)
; #define PG8_STAGE(bufoff, gbase, voff) do { _Pragma("unroll") for (int _i = 0; _i < 2; ++_i) glds16_s((voff)[_i], (const void*)(gbase), ldsbase + (unsigned)((bufoff) + _i * 8192) + ldsw); } while (0)
; template <class Epi, class Sched, bool HM = false>
; __device__ __forceinline__ void gemm_phase(PG8_LAS unsigned char* lds, const Gemm g, const Sched& S, const Epi& E) {
;     ...
;     const int tid = tid_, wid = __builtin_amdgcn_readfirstlane(tid >> 6), lane = tid & 63, wr = wid >> 2, wc = wid & 3, fr = lane & 15, fq = lane >> 4;
;     const int K = g.K, nt = K / BK;
;     unsigned voffA[2], voffB[2];
; #pragma unroll
;     for (int i = 0; i < 2; ++i) { int R, C; stage_rc(tid * 16 + i * 8192, R, C); const int Rb = Epi::PERM ? ((R & ~31) + perm32(R & 31)) : R;
;         voffA[i] = (unsigned)(R * g.lda + C) * 2u; voffB[i] = (unsigned)(Rb * g.ldb + C) * 2u; }
;     const unsigned voffX = (unsigned)((4 * (wid & 3) + (lane >> 4)) * g.lda + 8 * (lane & 15)) * 2u;
;     const size_t kstep = (size_t)(BK * 2);
;     const size_t hstepA = (size_t)HALF * g.lda * 2, hstepB = (size_t)HALF * g.ldb * 2;
;     const size_t tstepA = (size_t)(HM ? HALF : g.pms) * g.lda * 2, tstepB = 2 * hstepB, xstep = 2 * hstepA; const bool hasx = g.pms != BM;
;     const unsigned ldsw = (unsigned)wid * 1024u, ldsx = (unsigned)(wid & 3) * 1024u;
;     const unsigned ldsbase = (unsigned)__builtin_amdgcn_readfirstlane((int)(unsigned)(__UINTPTR_TYPE__)lds);
;     const int aoff = lds_byte(wr * 64 + fr, fq * 8), boff = lds_byte(wc * 32 + fr, fq * 8);
;     const int xoff = XOFF + fr * 256 + fq * 16;
;     ...
;     Unit cur, nxt; int ui = 0;
;     if (!S.next(0, cur)) return;
;     f32x4 acc[2][2][4][2]; f32x4 accx[2];
; #pragma unroll
;     for (int a = 0; a < 2; ++a)
; #pragma unroll
;         for (int b = 0; b < 2; ++b)
; #pragma unroll
;             for (int m = 0; m < 4; ++m)
; #pragma unroll
;                 for (int n = 0; n < 2; ++n) acc[a][b][m][n] = (f32x4){0.f, 0.f, 0.f, 0.f};
;     accx[0] = (f32x4){0.f, 0.f, 0.f, 0.f}; accx[1] = accx[0];
;     bf16x8 At[4][2], B0[2][2], B1[2][2], Ax[2];
;     const char* cA = PG8_APTR(cur); const char* cB = PG8_BPTR(cur);
;     S.a_ready(cur);
;     PG8_STAGE(PG8_SB(0, 0), cB, voffB); PG8_STAGE(PG8_SB(0, 1), cB + hstepB, voffB); PG8_STAGE(PG8_SA(0, 0), cA, voffA); PG8_STAGEX(0, cA + xstep); PG8_STAGE(PG8_SA(0, 1), cA + hstepA, voffA);
;     if (wr == 1) PG8_BAR;
.LBB0_237:
	s_mov_b64 s[0:1], s[30:31]
	s_mov_b64 s[4:5], s[30:31]
	s_mov_b64 s[8:9], s[30:31]
	s_waitcnt vmcnt(0)
	v_mov_b32_e32 v4, v0
	s_andn2_b64 vcc, exec, s[96:97]
	v_readfirstlane_b32 s20, v4
	s_cbranch_vccnz .LBB0_236
	v_bfe_i32 v7, v4, 27, 1
	v_lshlrev_b32_e32 v5, 4, v4
	v_lshrrev_b32_e32 v7, 22, v7
	v_add_u32_e32 v7, v5, v7
	v_and_b32_e32 v7, 0xfffffc00, v7
	v_sub_u32_e32 v7, v5, v7
	v_ashrrev_i32_e32 v6, 31, v4
	v_lshrrev_b32_e32 v8, 4, v7
	v_lshrrev_b32_e32 v6, 26, v6
	v_bitop3_b32 v7, v8, v7, 32 bitop3:0x6c
	v_add_u32_e32 v6, v4, v6
	v_ashrrev_i32_e32 v9, 31, v7
	v_ashrrev_i32_e32 v6, 6, v6
	v_lshrrev_b32_e32 v9, 26, v9
	v_lshlrev_b32_e32 v8, 3, v6
	v_add_u32_e32 v9, v7, v9
	v_and_b32_e32 v8, -16, v8
	v_ashrrev_i32_e32 v10, 6, v9
	v_and_b32_e32 v9, 0xc0, v9
	s_add_u32 s13, s0, 0x1a1e4000
	v_add_u32_e32 v8, v10, v8
	v_sub_u32_e32 v7, v7, v9
	s_addc_u32 s14, s1, 0
	v_lshlrev_b32_e32 v6, 5, v6
	v_ashrrev_i16_sdwa v7, v1, sext(v7) dst_sel:DWORD dst_unused:UNUSED_PAD src0_sel:DWORD src1_sel:BYTE_0
	v_lshlrev_b32_e32 v9, 1, v8
	v_lshrrev_b32_e32 v11, 2, v8
	v_and_b32_e32 v10, 3, v10
	s_mov_b32 s1, 0x3fffe0
	v_and_b32_e32 v6, 32, v6
	v_bfe_i32 v7, v7, 0, 16
	v_and_b32_e32 v9, 24, v9
	v_and_b32_e32 v11, 4, v11
	v_and_or_b32 v10, v8, s1, v10
	v_or3_b32 v9, v10, v11, v9
	v_add_lshl_u32 v6, v6, v7, 1
	v_add_u32_e32 v5, 0x2000, v5
	v_lshl_add_u32 v225, v8, 12, v6
	v_lshl_add_u32 v226, v9, 10, v6
	v_ashrrev_i32_e32 v6, 31, v5
	v_lshrrev_b32_e32 v6, 22, v6
	v_add_u32_e32 v6, v5, v6
	v_ashrrev_i32_e32 v6, 10, v6
	v_mul_i32_i24_e32 v7, 0x400, v6
	v_sub_u32_e32 v5, v5, v7
	v_lshrrev_b32_e32 v7, 4, v5
	v_bitop3_b32 v5, v7, v5, 32 bitop3:0x6c
	v_ashrrev_i32_e32 v8, 31, v5
	v_lshrrev_b32_e32 v8, 26, v8
	s_add_u32 s15, s4, 0x15aa0000
	v_lshlrev_b32_e32 v7, 3, v6
	v_add_u32_e32 v8, v5, v8
	s_addc_u32 s16, s5, 0
	s_ashr_i32 s0, s20, 6
	v_and_b32_e32 v7, -16, v7
	v_ashrrev_i32_e32 v9, 6, v8
	v_and_b32_e32 v8, 0xc0, v8
	s_and_b32 s21, s0, 3
	v_add_u32_e32 v7, v9, v7
	v_sub_u32_e32 v5, v5, v8
	v_and_b32_e32 v9, 3, v9
	v_lshlrev_b32_e32 v6, 5, v6
	v_ashrrev_i16_sdwa v5, v1, sext(v5) dst_sel:DWORD dst_unused:UNUSED_PAD src0_sel:DWORD src1_sel:BYTE_0
	v_lshlrev_b32_e32 v8, 1, v7
	v_lshrrev_b32_e32 v10, 2, v7
	v_and_or_b32 v9, v7, s1, v9
	s_ashr_i32 s22, s20, 8
	s_lshl_b32 s1, s21, 14
	s_lshl_b32 s0, s0, 10
	s_lshl_b32 s23, s21, 10
	v_readlane_b32 s4, v254, 34
	v_and_b32_e32 v6, 32, v6
	v_bfe_i32 v5, v5, 0, 16
	v_and_b32_e32 v8, 24, v8
	v_and_b32_e32 v10, 4, v10
	v_readlane_b32 s5, v254, 35
	s_add_u32 s4, s15, s4
	v_bfe_u32 v2, v4, 4, 2
	v_or3_b32 v8, v9, v10, v8
	v_add_lshl_u32 v5, v6, v5, 1
	v_and_b32_e32 v4, 15, v4
	s_addc_u32 s5, s16, s5
	s_add_i32 s17, s0, 0
	v_lshl_add_u32 v227, v7, 12, v5
	v_lshl_add_u32 v228, v8, 10, v5
	v_lshlrev_b32_e32 v5, 4, v4
	v_lshlrev_b32_e32 v6, 12, v2
	s_add_i32 s18, s17, 0x10000
	s_mov_b32 s0, m0
	s_mov_b32 m0, s18
	s_nop 0
	global_load_lds_dwordx4 v226, s[4:5]
	s_mov_b32 m0, s0
	v_or3_b32 v229, s1, v6, v5
	v_lshrrev_b32_e32 v232, 8, v229
	v_and_b32_e32 v232, 0xf0, v232
	v_xor_b32_e32 v229, v229, v232
	s_add_i32 s19, s17, 0x12000
	s_mov_b32 s0, m0
	s_mov_b32 m0, s19
	s_nop 0
	global_load_lds_dwordx4 v228, s[4:5]
	s_mov_b32 m0, s0
	v_readlane_b32 s1, v254, 23
	s_mul_i32 s0, s1, s10
	s_add_u32 s6, s13, s0
	s_mul_hi_i32 s0, s1, s10
	s_addc_u32 s7, s14, s0
	s_add_u32 s0, s4, 0x20000
	s_addc_u32 s1, s5, 0
	s_add_i32 s24, s17, 0x14000
	s_mov_b32 s25, m0
	s_mov_b32 m0, s24
	s_nop 0
	global_load_lds_dwordx4 v226, s[0:1]
	s_mov_b32 m0, s25
	s_add_i32 s25, s17, 0x16000
	s_mov_b32 s27, m0
	s_mov_b32 m0, s25
	s_nop 0
	global_load_lds_dwordx4 v228, s[0:1]
	s_mov_b32 m0, s27
	v_readlane_b32 s0, v254, 32
	v_readlane_b32 s1, v254, 33
	s_add_u32 s6, s6, s0
	s_addc_u32 s7, s7, s1
	s_mov_b32 s0, m0
	s_mov_b32 m0, s17
	s_nop 0
	global_load_lds_dwordx4 v225, s[6:7]
	s_mov_b32 m0, s0
	s_add_i32 s28, s17, 0x2000
	s_mov_b32 s0, m0
	s_mov_b32 m0, s28
	s_nop 0
	global_load_lds_dwordx4 v227, s[6:7]
	s_mov_b32 m0, s0
	s_add_u32 s0, s6, 0x100000
	s_addc_u32 s1, s7, 0
	s_add_i32 s29, s23, 0
	s_add_i32 s23, s29, 0x20400
	s_mov_b32 s27, m0
	s_mov_b32 m0, s23
	s_nop 0
	global_load_lds_dwordx4 v229, s[0:1]
	s_mov_b32 m0, s27
	s_add_u32 s0, s6, 0x80000
	s_addc_u32 s1, s7, 0
	s_add_i32 s30, s17, 0x4000
	s_mov_b32 s23, m0
	s_mov_b32 m0, s30
	s_nop 0
	global_load_lds_dwordx4 v225, s[0:1]
	s_mov_b32 m0, s23
	s_add_i32 s31, s17, 0x6000
	s_mov_b32 s23, m0
	s_mov_b32 m0, s31
	s_nop 0
	global_load_lds_dwordx4 v227, s[0:1]
	s_mov_b32 m0, s23
	s_cmp_eq_u32 s22, 1
	s_cselect_b64 s[0:1], -1, 0
	s_setprio 1
	s_cmp_lg_u32 s22, 1
	s_cbranch_scc1 .LBB0_240
	s_setprio 0
	s_barrier

; #define PG8_STAGE(bufoff, gbase, voff) do { _Pragma("unroll") for (int _i = 0; _i < 2; ++_i) glds16_s((voff)[_i], (const void*)(gbase), ldsbase + (unsigned)((bufoff) + _i * 8192) + ldsw); } while (0)
; template <class Epi, class Sched, bool HM = false>
; __device__ __forceinline__ void gemm_phase(PG8_LAS unsigned char* lds, const Gemm g, const Sched& S, const Epi& E) {
;     ...
;     const int tid = tid_, wid = __builtin_amdgcn_readfirstlane(tid >> 6), lane = tid & 63, wr = wid >> 2, wc = wid & 3, fr = lane & 15, fq = lane >> 4;
;     const int K = g.K, nt = K / BK;
;     unsigned voffA[2], voffB[2];
; #pragma unroll
;     for (int i = 0; i < 2; ++i) { int R, C; stage_rc(tid * 16 + i * 8192, R, C); const int Rb = Epi::PERM ? ((R & ~31) + perm32(R & 31)) : R;
;         voffA[i] = (unsigned)(R * g.lda + C) * 2u; voffB[i] = (unsigned)(Rb * g.ldb + C) * 2u; }
;     const unsigned voffX = (unsigned)((4 * (wid & 3) + (lane >> 4)) * g.lda + 8 * (lane & 15)) * 2u;
;     const size_t kstep = (size_t)(BK * 2);
;     const size_t hstepA = (size_t)HALF * g.lda * 2, hstepB = (size_t)HALF * g.ldb * 2;
;     const size_t tstepA = (size_t)(HM ? HALF : g.pms) * g.lda * 2, tstepB = 2 * hstepB, xstep = 2 * hstepA; const bool hasx = g.pms != BM;
;     const unsigned ldsw = (unsigned)wid * 1024u, ldsx = (unsigned)(wid & 3) * 1024u;
;     const unsigned ldsbase = (unsigned)__builtin_amdgcn_readfirstlane((int)(unsigned)(__UINTPTR_TYPE__)lds);
;     const int aoff = lds_byte(wr * 64 + fr, fq * 8), boff = lds_byte(wc * 32 + fr, fq * 8);
;     const int xoff = XOFF + fr * 256 + fq * 16;
;     ...
;     Unit cur, nxt; int ui = 0;
;     if (!S.next(0, cur)) return;
;     f32x4 acc[2][2][4][2]; f32x4 accx[2];
; #pragma unroll
;     for (int a = 0; a < 2; ++a)
; #pragma unroll
;         for (int b = 0; b < 2; ++b)
; #pragma unroll
;             for (int m = 0; m < 4; ++m)
; #pragma unroll
;                 for (int n = 0; n < 2; ++n) acc[a][b][m][n] = (f32x4){0.f, 0.f, 0.f, 0.f};
;     accx[0] = (f32x4){0.f, 0.f, 0.f, 0.f}; accx[1] = accx[0];
;     bf16x8 At[4][2], B0[2][2], B1[2][2], Ax[2];
;     const char* cA = PG8_APTR(cur); const char* cB = PG8_BPTR(cur);
;     S.a_ready(cur);
;     PG8_STAGE(PG8_SB(0, 0), cB, voffB); PG8_STAGE(PG8_SB(0, 1), cB + hstepB, voffB); PG8_STAGE(PG8_SA(0, 0), cA, voffA); PG8_STAGEX(0, cA + xstep); PG8_STAGE(PG8_SA(0, 1), cA + hstepA, voffA);
;     if (wr == 1) PG8_BAR;
.LBB0_515:
	s_mov_b64 s[0:1], s[30:31]
	s_mov_b64 s[4:5], s[30:31]
	s_mov_b64 s[8:9], s[30:31]
	s_waitcnt vmcnt(0)
	v_mov_b32_e32 v4, v0
	s_andn2_b64 vcc, exec, s[96:97]
	v_readfirstlane_b32 s20, v4
	s_cbranch_vccnz .LBB0_514
	v_bfe_i32 v7, v4, 27, 1
	v_lshlrev_b32_e32 v5, 4, v4
	v_lshrrev_b32_e32 v7, 22, v7
	v_add_u32_e32 v7, v5, v7
	v_and_b32_e32 v7, 0xfffffc00, v7
	v_sub_u32_e32 v7, v5, v7
	v_ashrrev_i32_e32 v6, 31, v4
	v_lshrrev_b32_e32 v8, 4, v7
	v_lshrrev_b32_e32 v6, 26, v6
	v_bitop3_b32 v7, v8, v7, 32 bitop3:0x6c
	s_add_u32 s14, s0, 0x1a1e4000
	v_add_u32_e32 v6, v4, v6
	v_ashrrev_i32_e32 v9, 31, v7
	s_addc_u32 s15, s1, 0
	v_ashrrev_i32_e32 v6, 6, v6
	v_lshrrev_b32_e32 v9, 26, v9
	s_add_u32 s0, s4, s12
	v_lshlrev_b32_e32 v8, 3, v6
	v_add_u32_e32 v9, v7, v9
	s_addc_u32 s1, s5, 0
	v_and_b32_e32 v8, -16, v8
	v_ashrrev_i32_e32 v10, 6, v9
	v_and_b32_e32 v9, 0xc0, v9
	s_add_u32 s16, s0, 0x42a0000
	v_add_u32_e32 v8, v10, v8
	v_sub_u32_e32 v7, v7, v9
	s_addc_u32 s17, s1, 0
	v_lshlrev_b32_e32 v6, 5, v6
	v_ashrrev_i16_sdwa v7, v1, sext(v7) dst_sel:DWORD dst_unused:UNUSED_PAD src0_sel:DWORD src1_sel:BYTE_0
	v_lshlrev_b32_e32 v9, 1, v8
	v_lshrrev_b32_e32 v11, 2, v8
	v_and_b32_e32 v10, 3, v10
	s_mov_b32 s1, 0xfffe0
	v_and_b32_e32 v6, 32, v6
	v_bfe_i32 v7, v7, 0, 16
	v_and_b32_e32 v9, 24, v9
	v_and_b32_e32 v11, 4, v11
	v_and_or_b32 v10, v8, s1, v10
	v_or3_b32 v9, v10, v11, v9
	v_add_lshl_u32 v6, v6, v7, 1
	v_add_u32_e32 v5, 0x2000, v5
	v_lshl_add_u32 v225, v8, 12, v6
	v_lshl_add_u32 v226, v9, 12, v6
	v_ashrrev_i32_e32 v6, 31, v5
	v_lshrrev_b32_e32 v6, 22, v6
	v_add_u32_e32 v6, v5, v6
	v_ashrrev_i32_e32 v6, 10, v6
	v_mul_i32_i24_e32 v7, 0x400, v6
	v_sub_u32_e32 v5, v5, v7
	v_lshrrev_b32_e32 v7, 4, v5
	v_bitop3_b32 v5, v7, v5, 32 bitop3:0x6c
	v_ashrrev_i32_e32 v8, 31, v5
	v_lshrrev_b32_e32 v8, 26, v8
	v_lshlrev_b32_e32 v7, 3, v6
	v_add_u32_e32 v8, v5, v8
	s_ashr_i32 s0, s20, 6
	v_and_b32_e32 v7, -16, v7
	v_ashrrev_i32_e32 v9, 6, v8
	v_and_b32_e32 v8, 0xc0, v8
	s_and_b32 s21, s0, 3
	v_add_u32_e32 v7, v9, v7
	v_sub_u32_e32 v5, v5, v8
	v_and_b32_e32 v9, 3, v9
	v_lshlrev_b32_e32 v6, 5, v6
	v_ashrrev_i16_sdwa v5, v1, sext(v5) dst_sel:DWORD dst_unused:UNUSED_PAD src0_sel:DWORD src1_sel:BYTE_0
	v_lshlrev_b32_e32 v8, 1, v7
	v_lshrrev_b32_e32 v10, 2, v7
	v_and_or_b32 v9, v7, s1, v9
	s_ashr_i32 s22, s20, 8
	s_lshl_b32 s1, s21, 14
	s_lshl_b32 s0, s0, 10
	s_lshl_b32 s23, s21, 10
	v_readlane_b32 s4, v254, 41
	v_and_b32_e32 v6, 32, v6
	v_bfe_i32 v5, v5, 0, 16
	v_and_b32_e32 v8, 24, v8
	v_and_b32_e32 v10, 4, v10
	v_readlane_b32 s5, v254, 42
	s_add_u32 s4, s16, s4
	v_bfe_u32 v2, v4, 4, 2
	v_or3_b32 v8, v9, v10, v8
	v_add_lshl_u32 v5, v6, v5, 1
	v_and_b32_e32 v4, 15, v4
	s_addc_u32 s5, s17, s5
	s_add_i32 s18, s0, 0
	v_lshl_add_u32 v227, v7, 12, v5
	v_lshl_add_u32 v228, v8, 12, v5
	v_lshlrev_b32_e32 v5, 4, v4
	v_lshlrev_b32_e32 v6, 12, v2
	s_add_i32 s19, s18, 0x10000
	s_mov_b32 s0, m0
	s_mov_b32 m0, s19
	s_nop 0
	global_load_lds_dwordx4 v226, s[4:5]
	s_mov_b32 m0, s0
	v_or3_b32 v229, s1, v6, v5
	v_lshrrev_b32_e32 v232, 8, v229
	v_and_b32_e32 v232, 0xf0, v232
	v_xor_b32_e32 v229, v229, v232
	s_add_i32 s24, s18, 0x12000
	s_mov_b32 s0, m0
	s_mov_b32 m0, s24
	s_nop 0
	global_load_lds_dwordx4 v228, s[4:5]
	s_mov_b32 m0, s0
	v_readlane_b32 s1, v254, 23
	s_mul_i32 s0, s1, s10
	s_add_u32 s6, s14, s0
	s_mul_hi_i32 s0, s1, s10
	s_addc_u32 s7, s15, s0
	s_add_u32 s0, s4, 0x80000
	s_addc_u32 s1, s5, 0
	s_add_i32 s25, s18, 0x14000
	s_mov_b32 s27, m0
	s_mov_b32 m0, s25
	s_nop 0
	global_load_lds_dwordx4 v226, s[0:1]
	s_mov_b32 m0, s27
	s_add_i32 s28, s18, 0x16000
	s_mov_b32 s27, m0
	s_mov_b32 m0, s28
	s_nop 0
	global_load_lds_dwordx4 v228, s[0:1]
	s_mov_b32 m0, s27
	v_readlane_b32 s0, v254, 38
	v_readlane_b32 s1, v254, 39
	s_add_u32 s6, s6, s0
	s_addc_u32 s7, s7, s1
	s_mov_b32 s0, m0
	s_mov_b32 m0, s18
	s_nop 0
	global_load_lds_dwordx4 v225, s[6:7]
	s_mov_b32 m0, s0
	s_add_i32 s29, s18, 0x2000
	s_mov_b32 s0, m0
	s_mov_b32 m0, s29
	s_nop 0
	global_load_lds_dwordx4 v227, s[6:7]
	s_mov_b32 m0, s0
	s_add_u32 s0, s6, 0x100000
	s_addc_u32 s1, s7, 0
	s_add_i32 s30, s23, 0
	s_add_i32 s23, s30, 0x20400
	s_mov_b32 s27, m0
	s_mov_b32 m0, s23
	s_nop 0
	global_load_lds_dwordx4 v229, s[0:1]
	s_mov_b32 m0, s27
	s_add_u32 s0, s6, 0x80000
	s_addc_u32 s1, s7, 0
	s_add_i32 s31, s18, 0x4000
	s_mov_b32 s23, m0
	s_mov_b32 m0, s31
	s_nop 0
	global_load_lds_dwordx4 v225, s[0:1]
	s_mov_b32 m0, s23
	s_add_i32 s36, s18, 0x6000
	s_mov_b32 s23, m0
	s_mov_b32 m0, s36
	s_nop 0
	global_load_lds_dwordx4 v227, s[0:1]
	s_mov_b32 m0, s23
	s_cmp_eq_u32 s22, 1
	s_cselect_b64 s[0:1], -1, 0
	s_setprio 1
	s_cmp_lg_u32 s22, 1
	s_cbranch_scc1 .LBB0_518
	s_setprio 0
	s_barrier

; #define PG8_STAGE(bufoff, gbase, voff) do { _Pragma("unroll") for (int _i = 0; _i < 2; ++_i) glds16_s((voff)[_i], (const void*)(gbase), ldsbase + (unsigned)((bufoff) + _i * 8192) + ldsw); } while (0)
; template <class Epi, class Sched, bool HM = false>
; __device__ __forceinline__ void gemm_phase(PG8_LAS unsigned char* lds, const Gemm g, const Sched& S, const Epi& E) {
;     ...
;     const int tid = tid_, wid = __builtin_amdgcn_readfirstlane(tid >> 6), lane = tid & 63, wr = wid >> 2, wc = wid & 3, fr = lane & 15, fq = lane >> 4;
;     const int K = g.K, nt = K / BK;
;     unsigned voffA[2], voffB[2];
; #pragma unroll
;     for (int i = 0; i < 2; ++i) { int R, C; stage_rc(tid * 16 + i * 8192, R, C); const int Rb = Epi::PERM ? ((R & ~31) + perm32(R & 31)) : R;
;         voffA[i] = (unsigned)(R * g.lda + C) * 2u; voffB[i] = (unsigned)(Rb * g.ldb + C) * 2u; }
;     const unsigned voffX = (unsigned)((4 * (wid & 3) + (lane >> 4)) * g.lda + 8 * (lane & 15)) * 2u;
;     const size_t kstep = (size_t)(BK * 2);
;     const size_t hstepA = (size_t)HALF * g.lda * 2, hstepB = (size_t)HALF * g.ldb * 2;
;     const size_t tstepA = (size_t)(HM ? HALF : g.pms) * g.lda * 2, tstepB = 2 * hstepB, xstep = 2 * hstepA; const bool hasx = g.pms != BM;
;     const unsigned ldsw = (unsigned)wid * 1024u, ldsx = (unsigned)(wid & 3) * 1024u;
;     const unsigned ldsbase = (unsigned)__builtin_amdgcn_readfirstlane((int)(unsigned)(__UINTPTR_TYPE__)lds);
;     const int aoff = lds_byte(wr * 64 + fr, fq * 8), boff = lds_byte(wc * 32 + fr, fq * 8);
;     const int xoff = XOFF + fr * 256 + fq * 16;
;     ...
;     Unit cur, nxt; int ui = 0;
;     if (!S.next(0, cur)) return;
;     f32x4 acc[2][2][4][2]; f32x4 accx[2];
; #pragma unroll
;     for (int a = 0; a < 2; ++a)
; #pragma unroll
;         for (int b = 0; b < 2; ++b)
; #pragma unroll
;             for (int m = 0; m < 4; ++m)
; #pragma unroll
;                 for (int n = 0; n < 2; ++n) acc[a][b][m][n] = (f32x4){0.f, 0.f, 0.f, 0.f};
;     accx[0] = (f32x4){0.f, 0.f, 0.f, 0.f}; accx[1] = accx[0];
;     bf16x8 At[4][2], B0[2][2], B1[2][2], Ax[2];
;     const char* cA = PG8_APTR(cur); const char* cB = PG8_BPTR(cur);
;     S.a_ready(cur);
;     PG8_STAGE(PG8_SB(0, 0), cB, voffB); PG8_STAGE(PG8_SB(0, 1), cB + hstepB, voffB); PG8_STAGE(PG8_SA(0, 0), cA, voffA); PG8_STAGEX(0, cA + xstep); PG8_STAGE(PG8_SA(0, 1), cA + hstepA, voffA);
;     if (wr == 1) PG8_BAR;
.LBB0_566:
	v_readlane_b32 s12, v254, 5
	s_mov_b64 s[4:5], s[30:31]
	s_mov_b64 s[6:7], s[30:31]
	s_mov_b64 s[38:39], s[30:31]
	s_mov_b64 s[34:35], s[30:31]
	s_mov_b64 s[8:9], s[30:31]
	s_mov_b64 s[0:1], s[30:31]
	s_waitcnt vmcnt(0)
	v_mov_b32_e32 v4, v0
	v_readlane_b32 s13, v254, 6
	s_andn2_b64 vcc, exec, s[12:13]
	v_readfirstlane_b32 s20, v4
	s_cbranch_vccnz .LBB0_616
	v_bfe_i32 v6, v4, 27, 1
	v_lshlrev_b32_e32 v2, 4, v4
	v_lshrrev_b32_e32 v6, 22, v6
	v_add_u32_e32 v6, v2, v6
	v_and_b32_e32 v6, 0xfffffc00, v6
	v_sub_u32_e32 v6, v2, v6
	v_ashrrev_i32_e32 v5, 31, v4
	v_lshrrev_b32_e32 v7, 4, v6
	v_lshrrev_b32_e32 v5, 26, v5
	v_bitop3_b32 v6, v7, v6, 32 bitop3:0x6c
	s_add_u32 s10, s4, 0x1a1e4000
	v_add_u32_e32 v5, v4, v5
	v_ashrrev_i32_e32 v8, 31, v6
	s_addc_u32 s14, s5, 0
	v_ashrrev_i32_e32 v5, 6, v5
	v_lshrrev_b32_e32 v8, 26, v8
	s_add_u32 s4, s6, s66
	v_lshlrev_b32_e32 v7, 3, v5
	v_add_u32_e32 v8, v6, v8
	s_addc_u32 s5, s7, s67
	v_and_b32_e32 v7, -16, v7
	v_ashrrev_i32_e32 v9, 6, v8
	v_and_b32_e32 v8, 0xc0, v8
	s_add_u32 s15, s4, 0xa0000
	v_add_u32_e32 v7, v9, v7
	v_sub_u32_e32 v6, v6, v8
	s_addc_u32 s45, s5, 0
	v_lshlrev_b32_e32 v5, 5, v5
	v_ashrrev_i16_sdwa v6, v1, sext(v6) dst_sel:DWORD dst_unused:UNUSED_PAD src0_sel:DWORD src1_sel:BYTE_0
	v_lshlrev_b32_e32 v8, 1, v7
	v_lshrrev_b32_e32 v10, 2, v7
	v_and_b32_e32 v9, 3, v9
	s_mov_b32 s5, 0xfffe0
	v_and_b32_e32 v5, 32, v5
	v_bfe_i32 v6, v6, 0, 16
	v_and_b32_e32 v8, 24, v8
	v_and_b32_e32 v10, 4, v10
	v_and_or_b32 v9, v7, s5, v9
	v_or3_b32 v8, v9, v10, v8
	v_add_lshl_u32 v5, v5, v6, 1
	v_add_u32_e32 v2, 0x2000, v2
	v_lshl_add_u32 v225, v7, 12, v5
	v_lshl_add_u32 v226, v8, 12, v5
	v_ashrrev_i32_e32 v5, 31, v2
	v_lshrrev_b32_e32 v5, 22, v5
	v_add_u32_e32 v5, v2, v5
	v_ashrrev_i32_e32 v5, 10, v5
	v_mul_i32_i24_e32 v6, 0x400, v5
	v_sub_u32_e32 v2, v2, v6
	v_lshrrev_b32_e32 v6, 4, v2
	v_bitop3_b32 v2, v6, v2, 32 bitop3:0x6c
	v_ashrrev_i32_e32 v7, 31, v2
	v_lshrrev_b32_e32 v7, 26, v7
	v_lshlrev_b32_e32 v6, 3, v5
	v_add_u32_e32 v7, v2, v7
	v_and_b32_e32 v6, -16, v6
	v_ashrrev_i32_e32 v8, 6, v7
	v_and_b32_e32 v7, 0xc0, v7
	v_add_u32_e32 v6, v8, v6
	v_sub_u32_e32 v2, v2, v7
	v_lshlrev_b32_e32 v5, 5, v5
	v_ashrrev_i16_sdwa v2, v1, sext(v2) dst_sel:DWORD dst_unused:UNUSED_PAD src0_sel:DWORD src1_sel:BYTE_0
	v_lshlrev_b32_e32 v7, 1, v6
	v_lshrrev_b32_e32 v9, 2, v6
	v_and_b32_e32 v8, 3, v8
	v_and_b32_e32 v5, 32, v5
	v_bfe_i32 v2, v2, 0, 16
	v_and_b32_e32 v7, 24, v7
	v_and_b32_e32 v9, 4, v9
	v_and_or_b32 v8, v6, s5, v8
	s_ashr_i32 s4, s20, 6
	v_or3_b32 v7, v8, v9, v7
	v_add_lshl_u32 v2, v5, v2, 1
	s_and_b32 s21, s4, 3
	v_lshl_add_u32 v227, v6, 12, v2
	v_lshl_add_u32 v228, v7, 12, v2
	v_and_b32_e32 v2, 15, v4
	v_bfe_u32 v4, v4, 4, 2
	s_lshl_b32 s5, s21, 14
	v_lshlrev_b32_e32 v5, 12, v4
	v_lshlrev_b32_e32 v6, 4, v2
	s_ashr_i32 s22, s20, 8
	v_or3_b32 v229, s5, v5, v6
	v_lshrrev_b32_e32 v232, 8, v229
	v_and_b32_e32 v232, 0xf0, v232
	v_xor_b32_e32 v229, v229, v232
	s_lshl_b32 s6, s4, 10
	s_lshl_b32 s18, s21, 10
	v_readlane_b32 s4, v254, 46
	v_readlane_b32 s5, v254, 47
	s_add_u32 s4, s15, s4
	s_addc_u32 s5, s45, s5
	s_add_i32 s51, s6, 0
	s_add_i32 s83, s51, 0x10000
	s_mov_b32 s6, m0
	s_mov_b32 m0, s83
	s_nop 0
	global_load_lds_dwordx4 v226, s[4:5]
	s_mov_b32 m0, s6
	s_add_i32 s36, s51, 0x12000
	s_mov_b32 s6, m0
	s_mov_b32 m0, s36
	s_nop 0
	global_load_lds_dwordx4 v228, s[4:5]
	s_mov_b32 m0, s6
	v_readlane_b32 s7, v254, 26
	s_mul_i32 s6, s7, s57
	s_add_u32 s12, s10, s6
	s_mul_hi_i32 s6, s7, s57
	s_addc_u32 s13, s14, s6
	s_add_u32 s6, s4, 0x80000
	s_addc_u32 s7, s5, 0
	s_add_i32 s37, s51, 0x14000
	s_mov_b32 s16, m0
	s_mov_b32 m0, s37
	s_nop 0
	global_load_lds_dwordx4 v226, s[6:7]
	s_mov_b32 m0, s16
	s_add_i32 s16, s51, 0x16000
	s_mov_b32 s17, m0
	s_mov_b32 m0, s16
	s_nop 0
	global_load_lds_dwordx4 v228, s[6:7]
	s_mov_b32 m0, s17
	v_readlane_b32 s6, v254, 43
	v_readlane_b32 s7, v254, 44
	s_add_u32 s6, s12, s6
	s_addc_u32 s7, s13, s7
	s_mov_b32 s12, m0
	s_mov_b32 m0, s51
	s_nop 0
	global_load_lds_dwordx4 v225, s[6:7]
	s_mov_b32 m0, s12
	s_add_i32 s17, s51, 0x2000
	s_mov_b32 s12, m0
	s_mov_b32 m0, s17
	s_nop 0
	global_load_lds_dwordx4 v227, s[6:7]
	s_mov_b32 m0, s12
	s_add_u32 s12, s6, 0x100000
	s_addc_u32 s13, s7, 0
	s_add_i32 s18, s18, 0
	s_add_i32 s19, s18, 0x20400
	s_mov_b32 s23, m0
	s_mov_b32 m0, s19
	s_nop 0
	global_load_lds_dwordx4 v229, s[12:13]
	s_mov_b32 m0, s23
	s_add_u32 s12, s6, 0x80000
	s_addc_u32 s13, s7, 0
	s_add_i32 s19, s51, 0x4000
	s_mov_b32 s23, m0
	s_mov_b32 m0, s19
	s_nop 0
	global_load_lds_dwordx4 v225, s[12:13]
	s_mov_b32 m0, s23
	s_add_i32 s28, s51, 0x6000
	s_mov_b32 s23, m0
	s_mov_b32 m0, s28
	s_nop 0
	global_load_lds_dwordx4 v227, s[12:13]
	s_mov_b32 m0, s23
	s_cmp_eq_u32 s22, 1
	s_cselect_b64 s[74:75], -1, 0
	s_setprio 1
	s_cmp_lg_u32 s22, 1
	s_cbranch_scc1 .LBB0_569
	s_setprio 0
	s_barrier

; #define PG8_STAGE(bufoff, gbase, voff) do { _Pragma("unroll") for (int _i = 0; _i < 2; ++_i) glds16_s((voff)[_i], (const void*)(gbase), ldsbase + (unsigned)((bufoff) + _i * 8192) + ldsw); } while (0)
; template <class Epi, class Sched, bool HM = false>
; __device__ __forceinline__ void gemm_phase(PG8_LAS unsigned char* lds, const Gemm g, const Sched& S, const Epi& E) {
;     ...
;     const int tid = tid_, wid = __builtin_amdgcn_readfirstlane(tid >> 6), lane = tid & 63, wr = wid >> 2, wc = wid & 3, fr = lane & 15, fq = lane >> 4;
;     const int K = g.K, nt = K / BK;
;     unsigned voffA[2], voffB[2];
; #pragma unroll
;     for (int i = 0; i < 2; ++i) { int R, C; stage_rc(tid * 16 + i * 8192, R, C); const int Rb = Epi::PERM ? ((R & ~31) + perm32(R & 31)) : R;
;         voffA[i] = (unsigned)(R * g.lda + C) * 2u; voffB[i] = (unsigned)(Rb * g.ldb + C) * 2u; }
;     const unsigned voffX = (unsigned)((4 * (wid & 3) + (lane >> 4)) * g.lda + 8 * (lane & 15)) * 2u;
;     const size_t kstep = (size_t)(BK * 2);
;     const size_t hstepA = (size_t)HALF * g.lda * 2, hstepB = (size_t)HALF * g.ldb * 2;
;     const size_t tstepA = (size_t)(HM ? HALF : g.pms) * g.lda * 2, tstepB = 2 * hstepB, xstep = 2 * hstepA; const bool hasx = g.pms != BM;
;     const unsigned ldsw = (unsigned)wid * 1024u, ldsx = (unsigned)(wid & 3) * 1024u;
;     const unsigned ldsbase = (unsigned)__builtin_amdgcn_readfirstlane((int)(unsigned)(__UINTPTR_TYPE__)lds);
;     const int aoff = lds_byte(wr * 64 + fr, fq * 8), boff = lds_byte(wc * 32 + fr, fq * 8);
;     const int xoff = XOFF + fr * 256 + fq * 16;
;     ...
;     Unit cur, nxt; int ui = 0;
;     if (!S.next(0, cur)) return;
;     f32x4 acc[2][2][4][2]; f32x4 accx[2];
; #pragma unroll
;     for (int a = 0; a < 2; ++a)
; #pragma unroll
;         for (int b = 0; b < 2; ++b)
; #pragma unroll
;             for (int m = 0; m < 4; ++m)
; #pragma unroll
;                 for (int n = 0; n < 2; ++n) acc[a][b][m][n] = (f32x4){0.f, 0.f, 0.f, 0.f};
;     accx[0] = (f32x4){0.f, 0.f, 0.f, 0.f}; accx[1] = accx[0];
;     bf16x8 At[4][2], B0[2][2], B1[2][2], Ax[2];
;     const char* cA = PG8_APTR(cur); const char* cB = PG8_BPTR(cur);
;     S.a_ready(cur);
;     PG8_STAGE(PG8_SB(0, 0), cB, voffB); PG8_STAGE(PG8_SB(0, 1), cB + hstepB, voffB); PG8_STAGE(PG8_SA(0, 0), cA, voffA); PG8_STAGEX(0, cA + xstep); PG8_STAGE(PG8_SA(0, 1), cA + hstepA, voffA);
;     if (wr == 1) PG8_BAR;
.LBB0_968:
	s_mov_b64 s[0:1], s[30:31]
	s_mov_b64 s[4:5], s[30:31]
	s_mov_b64 s[8:9], s[30:31]
	v_mov_b32_e32 v4, v0
	s_andn2_b64 vcc, exec, s[96:97]
	v_readfirstlane_b32 s20, v4
	s_cbranch_vccnz .LBB0_967
	v_bfe_i32 v7, v4, 27, 1
	v_lshlrev_b32_e32 v5, 4, v4
	v_lshrrev_b32_e32 v7, 22, v7
	v_add_u32_e32 v7, v5, v7
	v_and_b32_e32 v7, 0xfffffc00, v7
	v_sub_u32_e32 v7, v5, v7
	v_ashrrev_i32_e32 v6, 31, v4
	v_lshrrev_b32_e32 v8, 4, v7
	v_lshrrev_b32_e32 v6, 26, v6
	v_bitop3_b32 v7, v8, v7, 32 bitop3:0x6c
	s_add_u32 s14, s0, 0x1a1e4000
	v_add_u32_e32 v6, v4, v6
	v_ashrrev_i32_e32 v9, 31, v7
	s_addc_u32 s15, s1, 0
	v_ashrrev_i32_e32 v6, 6, v6
	v_lshrrev_b32_e32 v9, 26, v9
	s_add_u32 s0, s4, s12
	v_lshlrev_b32_e32 v8, 3, v6
	v_add_u32_e32 v9, v7, v9
	s_addc_u32 s1, s5, 0
	v_and_b32_e32 v8, -16, v8
	v_ashrrev_i32_e32 v10, 6, v9
	v_and_b32_e32 v9, 0xc0, v9
	s_add_u32 s16, s0, 0x32a0000
	v_add_u32_e32 v8, v10, v8
	v_sub_u32_e32 v7, v7, v9
	s_addc_u32 s17, s1, 0
	v_lshlrev_b32_e32 v6, 5, v6
	v_ashrrev_i16_sdwa v7, v1, sext(v7) dst_sel:DWORD dst_unused:UNUSED_PAD src0_sel:DWORD src1_sel:BYTE_0
	v_lshlrev_b32_e32 v9, 1, v8
	v_lshrrev_b32_e32 v11, 2, v8
	v_and_b32_e32 v10, 3, v10
	s_mov_b32 s1, 0xfffe0
	v_and_b32_e32 v6, 32, v6
	v_bfe_i32 v7, v7, 0, 16
	v_and_b32_e32 v9, 24, v9
	v_and_b32_e32 v11, 4, v11
	v_and_or_b32 v10, v8, s1, v10
	v_or3_b32 v9, v10, v11, v9
	v_add_lshl_u32 v6, v6, v7, 1
	v_add_u32_e32 v5, 0x2000, v5
	v_lshl_add_u32 v225, v8, 12, v6
	v_lshl_add_u32 v226, v9, 12, v6
	v_ashrrev_i32_e32 v6, 31, v5
	v_lshrrev_b32_e32 v6, 22, v6
	v_add_u32_e32 v6, v5, v6
	v_ashrrev_i32_e32 v6, 10, v6
	v_mul_i32_i24_e32 v7, 0x400, v6
	v_sub_u32_e32 v5, v5, v7
	v_lshrrev_b32_e32 v7, 4, v5
	v_bitop3_b32 v5, v7, v5, 32 bitop3:0x6c
	v_ashrrev_i32_e32 v8, 31, v5
	v_lshrrev_b32_e32 v8, 26, v8
	v_lshlrev_b32_e32 v7, 3, v6
	v_add_u32_e32 v8, v5, v8
	s_ashr_i32 s0, s20, 6
	v_and_b32_e32 v7, -16, v7
	v_ashrrev_i32_e32 v9, 6, v8
	v_and_b32_e32 v8, 0xc0, v8
	s_and_b32 s21, s0, 3
	v_add_u32_e32 v7, v9, v7
	v_sub_u32_e32 v5, v5, v8
	v_and_b32_e32 v9, 3, v9
	v_lshlrev_b32_e32 v6, 5, v6
	v_ashrrev_i16_sdwa v5, v1, sext(v5) dst_sel:DWORD dst_unused:UNUSED_PAD src0_sel:DWORD src1_sel:BYTE_0
	v_lshlrev_b32_e32 v8, 1, v7
	v_lshrrev_b32_e32 v10, 2, v7
	v_and_or_b32 v9, v7, s1, v9
	s_ashr_i32 s22, s20, 8
	s_lshl_b32 s1, s21, 14
	s_lshl_b32 s0, s0, 10
	s_lshl_b32 s23, s21, 10
	v_readlane_b32 s4, v254, 41
	v_and_b32_e32 v6, 32, v6
	v_bfe_i32 v5, v5, 0, 16
	v_and_b32_e32 v8, 24, v8
	v_and_b32_e32 v10, 4, v10
	v_readlane_b32 s5, v254, 42
	s_add_u32 s4, s16, s4
	v_bfe_u32 v2, v4, 4, 2
	v_or3_b32 v8, v9, v10, v8
	v_add_lshl_u32 v5, v6, v5, 1
	v_and_b32_e32 v4, 15, v4
	s_addc_u32 s5, s17, s5
	s_add_i32 s18, s0, 0
	v_lshl_add_u32 v227, v7, 12, v5
	v_lshl_add_u32 v228, v8, 12, v5
	v_lshlrev_b32_e32 v5, 4, v4
	v_lshlrev_b32_e32 v6, 12, v2
	s_add_i32 s19, s18, 0x10000
	s_mov_b32 s0, m0
	s_mov_b32 m0, s19
	s_nop 0
	global_load_lds_dwordx4 v226, s[4:5]
	s_mov_b32 m0, s0
	v_or3_b32 v229, s1, v6, v5
	v_lshrrev_b32_e32 v232, 8, v229
	v_and_b32_e32 v232, 0xf0, v232
	v_xor_b32_e32 v229, v229, v232
	s_add_i32 s24, s18, 0x12000
	s_mov_b32 s0, m0
	s_mov_b32 m0, s24
	s_nop 0
	global_load_lds_dwordx4 v228, s[4:5]
	s_mov_b32 m0, s0
	v_readlane_b32 s1, v254, 23
	s_mul_i32 s0, s1, s10
	s_add_u32 s6, s14, s0
	s_mul_hi_i32 s0, s1, s10
	s_addc_u32 s7, s15, s0
	s_add_u32 s0, s4, 0x80000
	s_addc_u32 s1, s5, 0
	s_add_i32 s25, s18, 0x14000
	s_mov_b32 s27, m0
	s_mov_b32 m0, s25
	s_nop 0
	global_load_lds_dwordx4 v226, s[0:1]
	s_mov_b32 m0, s27
	s_add_i32 s28, s18, 0x16000
	s_mov_b32 s27, m0
	s_mov_b32 m0, s28
	s_nop 0
	global_load_lds_dwordx4 v228, s[0:1]
	s_mov_b32 m0, s27
	v_readlane_b32 s0, v254, 38
	v_readlane_b32 s1, v254, 39
	s_add_u32 s6, s6, s0
	s_addc_u32 s7, s7, s1
	s_mov_b32 s0, m0
	s_mov_b32 m0, s18
	s_nop 0
	global_load_lds_dwordx4 v225, s[6:7]
	s_mov_b32 m0, s0
	s_add_i32 s29, s18, 0x2000
	s_mov_b32 s0, m0
	s_mov_b32 m0, s29
	s_nop 0
	global_load_lds_dwordx4 v227, s[6:7]
	s_mov_b32 m0, s0
	s_add_u32 s0, s6, 0x100000
	s_addc_u32 s1, s7, 0
	s_add_i32 s30, s23, 0
	s_add_i32 s23, s30, 0x20400
	s_mov_b32 s27, m0
	s_mov_b32 m0, s23
	s_nop 0
	global_load_lds_dwordx4 v229, s[0:1]
	s_mov_b32 m0, s27
	s_add_u32 s0, s6, 0x80000
	s_addc_u32 s1, s7, 0
	s_add_i32 s31, s18, 0x4000
	s_mov_b32 s23, m0
	s_mov_b32 m0, s31
	s_nop 0
	global_load_lds_dwordx4 v225, s[0:1]
	s_mov_b32 m0, s23
	s_add_i32 s36, s18, 0x6000
	s_mov_b32 s23, m0
	s_mov_b32 m0, s36
	s_nop 0
	global_load_lds_dwordx4 v227, s[0:1]
	s_mov_b32 m0, s23
	s_cmp_eq_u32 s22, 1
	s_cselect_b64 s[0:1], -1, 0
	s_setprio 1
	s_cmp_lg_u32 s22, 1
	s_cbranch_scc1 .LBB0_971
	s_setprio 0
	s_barrier

; #define PG8_STAGE(bufoff, gbase, voff) do { _Pragma("unroll") for (int _i = 0; _i < 2; ++_i) glds16_s((voff)[_i], (const void*)(gbase), ldsbase + (unsigned)((bufoff) + _i * 8192) + ldsw); } while (0)
; template <class Epi, class Sched, bool HM = false>
; __device__ __forceinline__ void gemm_phase(PG8_LAS unsigned char* lds, const Gemm g, const Sched& S, const Epi& E) {
;     ...
;     const int tid = tid_, wid = __builtin_amdgcn_readfirstlane(tid >> 6), lane = tid & 63, wr = wid >> 2, wc = wid & 3, fr = lane & 15, fq = lane >> 4;
;     const int K = g.K, nt = K / BK;
;     unsigned voffA[2], voffB[2];
; #pragma unroll
;     for (int i = 0; i < 2; ++i) { int R, C; stage_rc(tid * 16 + i * 8192, R, C); const int Rb = Epi::PERM ? ((R & ~31) + perm32(R & 31)) : R;
;         voffA[i] = (unsigned)(R * g.lda + C) * 2u; voffB[i] = (unsigned)(Rb * g.ldb + C) * 2u; }
;     const unsigned voffX = (unsigned)((4 * (wid & 3) + (lane >> 4)) * g.lda + 8 * (lane & 15)) * 2u;
;     const size_t kstep = (size_t)(BK * 2);
;     const size_t hstepA = (size_t)HALF * g.lda * 2, hstepB = (size_t)HALF * g.ldb * 2;
;     const size_t tstepA = (size_t)(HM ? HALF : g.pms) * g.lda * 2, tstepB = 2 * hstepB, xstep = 2 * hstepA; const bool hasx = g.pms != BM;
;     const unsigned ldsw = (unsigned)wid * 1024u, ldsx = (unsigned)(wid & 3) * 1024u;
;     const unsigned ldsbase = (unsigned)__builtin_amdgcn_readfirstlane((int)(unsigned)(__UINTPTR_TYPE__)lds);
;     const int aoff = lds_byte(wr * 64 + fr, fq * 8), boff = lds_byte(wc * 32 + fr, fq * 8);
;     const int xoff = XOFF + fr * 256 + fq * 16;
;     ...
;     Unit cur, nxt; int ui = 0;
;     if (!S.next(0, cur)) return;
;     f32x4 acc[2][2][4][2]; f32x4 accx[2];
; #pragma unroll
;     for (int a = 0; a < 2; ++a)
; #pragma unroll
;         for (int b = 0; b < 2; ++b)
; #pragma unroll
;             for (int m = 0; m < 4; ++m)
; #pragma unroll
;                 for (int n = 0; n < 2; ++n) acc[a][b][m][n] = (f32x4){0.f, 0.f, 0.f, 0.f};
;     accx[0] = (f32x4){0.f, 0.f, 0.f, 0.f}; accx[1] = accx[0];
;     bf16x8 At[4][2], B0[2][2], B1[2][2], Ax[2];
;     const char* cA = PG8_APTR(cur); const char* cB = PG8_BPTR(cur);
;     S.a_ready(cur);
;     PG8_STAGE(PG8_SB(0, 0), cB, voffB); PG8_STAGE(PG8_SB(0, 1), cB + hstepB, voffB); PG8_STAGE(PG8_SA(0, 0), cA, voffA); PG8_STAGEX(0, cA + xstep); PG8_STAGE(PG8_SA(0, 1), cA + hstepA, voffA);
;     if (wr == 1) PG8_BAR;
.LBB0_1149:
	s_mov_b64 s[0:1], s[30:31]
	s_mov_b64 s[4:5], s[30:31]
	s_mov_b64 s[6:7], s[30:31]
	v_mov_b32_e32 v5, v0
	s_andn2_b64 vcc, exec, s[70:71]
	v_readfirstlane_b32 s8, v5
	s_cbranch_vccnz .LBB0_1169
	v_bfe_i32 v6, v5, 27, 1
	v_lshlrev_b32_e32 v4, 4, v5
	v_lshrrev_b32_e32 v6, 22, v6
	v_add_u32_e32 v6, v4, v6
	v_and_b32_e32 v6, 0xfffffc00, v6
	v_sub_u32_e32 v6, v4, v6
	v_ashrrev_i32_e32 v2, 31, v5
	v_lshrrev_b32_e32 v7, 4, v6
	v_lshrrev_b32_e32 v2, 26, v2
	v_bitop3_b32 v6, v7, v6, 32 bitop3:0x6c
	s_add_u32 s34, s0, 0x1a1e4000
	v_add_u32_e32 v2, v5, v2
	v_ashrrev_i32_e32 v8, 31, v6
	s_addc_u32 s35, s1, 0
	v_readlane_b32 s0, v255, 25
	v_ashrrev_i32_e32 v2, 6, v2
	v_lshrrev_b32_e32 v8, 26, v8
	s_add_u32 s0, s4, s0
	v_lshlrev_b32_e32 v7, 3, v2
	v_add_u32_e32 v8, v6, v8
	s_addc_u32 s1, s5, s89
	v_and_b32_e32 v7, -16, v7
	v_ashrrev_i32_e32 v9, 6, v8
	v_and_b32_e32 v8, 0xc0, v8
	s_add_u32 s43, s0, 0x52a0000
	v_add_u32_e32 v7, v9, v7
	v_sub_u32_e32 v6, v6, v8
	s_addc_u32 s46, s1, 0
	v_lshlrev_b32_e32 v2, 5, v2
	v_ashrrev_i16_sdwa v6, v1, sext(v6) dst_sel:DWORD dst_unused:UNUSED_PAD src0_sel:DWORD src1_sel:BYTE_0
	v_lshlrev_b32_e32 v8, 1, v7
	v_lshrrev_b32_e32 v10, 2, v7
	v_and_b32_e32 v9, 3, v9
	s_mov_b32 s1, 0xfffe0
	v_and_b32_e32 v2, 32, v2
	v_bfe_i32 v6, v6, 0, 16
	v_and_b32_e32 v8, 24, v8
	v_and_b32_e32 v10, 4, v10
	v_and_or_b32 v9, v7, s1, v9
	v_or3_b32 v8, v9, v10, v8
	v_add_lshl_u32 v6, v2, v6, 1
	v_add_u32_e32 v4, 0x2000, v4
	v_lshl_add_u32 v2, v7, 12, v6
	v_lshl_add_u32 v134, v8, 12, v6
	v_ashrrev_i32_e32 v6, 31, v4
	v_lshrrev_b32_e32 v6, 22, v6
	v_add_u32_e32 v6, v4, v6
	v_ashrrev_i32_e32 v6, 10, v6
	v_mul_i32_i24_e32 v7, 0x400, v6
	v_sub_u32_e32 v4, v4, v7
	v_lshrrev_b32_e32 v7, 4, v4
	v_bitop3_b32 v4, v7, v4, 32 bitop3:0x6c
	v_ashrrev_i32_e32 v8, 31, v4
	v_lshrrev_b32_e32 v8, 26, v8
	v_lshlrev_b32_e32 v7, 3, v6
	v_add_u32_e32 v8, v4, v8
	v_and_b32_e32 v7, -16, v7
	v_ashrrev_i32_e32 v9, 6, v8
	v_and_b32_e32 v8, 0xc0, v8
	v_add_u32_e32 v7, v9, v7
	v_sub_u32_e32 v4, v4, v8
	v_lshlrev_b32_e32 v6, 5, v6
	v_ashrrev_i16_sdwa v4, v1, sext(v4) dst_sel:DWORD dst_unused:UNUSED_PAD src0_sel:DWORD src1_sel:BYTE_0
	v_lshlrev_b32_e32 v8, 1, v7
	v_lshrrev_b32_e32 v10, 2, v7
	v_and_b32_e32 v9, 3, v9
	v_and_b32_e32 v6, 32, v6
	v_bfe_i32 v4, v4, 0, 16
	v_and_b32_e32 v8, 24, v8
	v_and_b32_e32 v10, 4, v10
	v_and_or_b32 v9, v7, s1, v9
	s_ashr_i32 s0, s8, 6
	v_or3_b32 v8, v9, v10, v8
	v_add_lshl_u32 v4, v6, v4, 1
	s_and_b32 s9, s0, 3
	v_lshl_add_u32 v135, v7, 12, v4
	v_lshl_add_u32 v136, v8, 12, v4
	v_and_b32_e32 v4, 15, v5
	v_bfe_u32 v5, v5, 4, 2
	s_lshl_b32 s1, s9, 14
	v_lshlrev_b32_e32 v6, 12, v5
	v_lshlrev_b32_e32 v7, 4, v4
	s_ashr_i32 s12, s8, 8
	v_or3_b32 v137, s1, v6, v7
	s_lshl_b32 s4, s0, 10
	s_lshl_b32 s13, s9, 10
	s_mov_b64 s[0:1], s[68:69]
	s_add_u32 s0, s43, s0
	s_addc_u32 s1, s46, s1
	s_add_i32 s47, s4, 0
	s_add_i32 s90, s47, 0x10000
	s_mov_b32 s4, m0
	s_mov_b32 m0, s90
	s_nop 0
	global_load_lds_dwordx4 v134, s[0:1]
	s_mov_b32 m0, s4
	s_add_i32 s91, s47, 0x12000
	s_mov_b32 s4, m0
	s_mov_b32 m0, s91
	s_nop 0
	global_load_lds_dwordx4 v136, s[0:1]
	s_mov_b32 m0, s4
	s_nop 0
	v_readlane_b32 s4, v255, 23
	v_readlane_b32 s5, v255, 24
	s_add_u32 s14, s34, s4
	s_addc_u32 s15, s35, s5
	s_add_u32 s4, s0, 0x80000
	s_addc_u32 s5, s1, 0
	s_add_i32 s92, s47, 0x14000
	s_mov_b32 s16, m0
	s_mov_b32 m0, s92
	s_nop 0
	global_load_lds_dwordx4 v134, s[4:5]
	s_mov_b32 m0, s16
	s_add_i32 s20, s47, 0x16000
	s_mov_b32 s16, m0
	s_mov_b32 m0, s20
	s_nop 0
	global_load_lds_dwordx4 v136, s[4:5]
	s_mov_b32 m0, s16
	s_mov_b64 s[4:5], s[66:67]
	s_add_u32 s4, s14, s4
	s_addc_u32 s5, s15, s5
	s_mov_b32 s14, m0
	s_mov_b32 m0, s47
	s_nop 0
	global_load_lds_dwordx4 v2, s[4:5]
	s_mov_b32 m0, s14
	s_add_i32 s21, s47, 0x2000
	s_mov_b32 s14, m0
	s_mov_b32 m0, s21
	s_nop 0
	global_load_lds_dwordx4 v135, s[4:5]
	s_mov_b32 m0, s14
	s_add_u32 s14, s4, 0x100000
	s_addc_u32 s15, s5, 0
	s_add_i32 s97, s13, 0
	s_add_i32 s13, s97, 0x20400
	s_mov_b32 s16, m0
	s_mov_b32 m0, s13
	s_nop 0
	global_load_lds_dwordx4 v137, s[14:15]
	s_mov_b32 m0, s16
	s_add_u32 s14, s4, 0x80000
	s_addc_u32 s15, s5, 0
	s_add_i32 s42, s47, 0x4000
	s_mov_b32 s13, m0
	s_mov_b32 m0, s42
	s_nop 0
	global_load_lds_dwordx4 v2, s[14:15]
	s_mov_b32 m0, s13
	s_add_i32 s40, s47, 0x6000
	s_mov_b32 s13, m0
	s_mov_b32 m0, s40
	s_nop 0
	global_load_lds_dwordx4 v135, s[14:15]
	s_mov_b32 m0, s13
	s_cmp_eq_u32 s12, 1
	s_cselect_b64 s[62:63], -1, 0
	s_setprio 1
	s_cmp_lg_u32 s12, 1
	s_cbranch_scc1 .LBB0_1152
	s_setprio 0
	s_barrier

; #define PG8_STAGE(bufoff, gbase, voff) do { _Pragma("unroll") for (int _i = 0; _i < 2; ++_i) glds16_s((voff)[_i], (const void*)(gbase), ldsbase + (unsigned)((bufoff) + _i * 8192) + ldsw); } while (0)
; template <class Epi, class Sched, bool HM = false>
; __device__ __forceinline__ void gemm_phase(PG8_LAS unsigned char* lds, const Gemm g, const Sched& S, const Epi& E) {
;     ...
;     const int tid = tid_, wid = __builtin_amdgcn_readfirstlane(tid >> 6), lane = tid & 63, wr = wid >> 2, wc = wid & 3, fr = lane & 15, fq = lane >> 4;
;     const int K = g.K, nt = K / BK;
;     unsigned voffA[2], voffB[2];
; #pragma unroll
;     for (int i = 0; i < 2; ++i) { int R, C; stage_rc(tid * 16 + i * 8192, R, C); const int Rb = Epi::PERM ? ((R & ~31) + perm32(R & 31)) : R;
;         voffA[i] = (unsigned)(R * g.lda + C) * 2u; voffB[i] = (unsigned)(Rb * g.ldb + C) * 2u; }
;     const unsigned voffX = (unsigned)((4 * (wid & 3) + (lane >> 4)) * g.lda + 8 * (lane & 15)) * 2u;
;     const size_t kstep = (size_t)(BK * 2);
;     const size_t hstepA = (size_t)HALF * g.lda * 2, hstepB = (size_t)HALF * g.ldb * 2;
;     const size_t tstepA = (size_t)(HM ? HALF : g.pms) * g.lda * 2, tstepB = 2 * hstepB, xstep = 2 * hstepA; const bool hasx = g.pms != BM;
;     const unsigned ldsw = (unsigned)wid * 1024u, ldsx = (unsigned)(wid & 3) * 1024u;
;     const unsigned ldsbase = (unsigned)__builtin_amdgcn_readfirstlane((int)(unsigned)(__UINTPTR_TYPE__)lds);
;     const int aoff = lds_byte(wr * 64 + fr, fq * 8), boff = lds_byte(wc * 32 + fr, fq * 8);
;     const int xoff = XOFF + fr * 256 + fq * 16;
;     ...
;     Unit cur, nxt; int ui = 0;
;     if (!S.next(0, cur)) return;
;     f32x4 acc[2][2][4][2]; f32x4 accx[2];
; #pragma unroll
;     for (int a = 0; a < 2; ++a)
; #pragma unroll
;         for (int b = 0; b < 2; ++b)
; #pragma unroll
;             for (int m = 0; m < 4; ++m)
; #pragma unroll
;                 for (int n = 0; n < 2; ++n) acc[a][b][m][n] = (f32x4){0.f, 0.f, 0.f, 0.f};
;     accx[0] = (f32x4){0.f, 0.f, 0.f, 0.f}; accx[1] = accx[0];
;     bf16x8 At[4][2], B0[2][2], B1[2][2], Ax[2];
;     const char* cA = PG8_APTR(cur); const char* cB = PG8_BPTR(cur);
;     S.a_ready(cur);
;     PG8_STAGE(PG8_SB(0, 0), cB, voffB); PG8_STAGE(PG8_SB(0, 1), cB + hstepB, voffB); PG8_STAGE(PG8_SA(0, 0), cA, voffA); PG8_STAGEX(0, cA + xstep); PG8_STAGE(PG8_SA(0, 1), cA + hstepA, voffA);
;     if (wr == 1) PG8_BAR;
.LBB0_1169:
	v_readlane_b32 s0, v255, 18
	v_readlane_b32 s1, v255, 19
	s_andn2_b64 vcc, exec, s[0:1]
	s_cbranch_vccnz .LBB0_1148
	v_readlane_b32 s6, v255, 5
	s_mov_b64 s[0:1], s[30:31]
	s_mov_b64 s[4:5], s[30:31]
	s_mov_b64 s[8:9], s[30:31]
	v_mov_b32_e32 v5, v0
	v_readlane_b32 s7, v255, 6
	s_andn2_b64 vcc, exec, s[6:7]
	v_readfirstlane_b32 s22, v5
	s_cbranch_vccnz .LBB0_1148
	v_bfe_i32 v6, v5, 27, 1
	v_lshlrev_b32_e32 v4, 4, v5
	v_lshrrev_b32_e32 v6, 22, v6
	v_add_u32_e32 v6, v4, v6
	v_and_b32_e32 v6, 0xfffffc00, v6
	v_sub_u32_e32 v6, v4, v6
	v_ashrrev_i32_e32 v2, 31, v5
	v_lshrrev_b32_e32 v7, 4, v6
	v_lshrrev_b32_e32 v2, 26, v2
	v_bitop3_b32 v6, v7, v6, 32 bitop3:0x6c
	s_add_u32 s12, s0, 0x1a1e4000
	v_add_u32_e32 v2, v5, v2
	v_ashrrev_i32_e32 v8, 31, v6
	s_addc_u32 s13, s1, 0
	v_readlane_b32 s0, v255, 25
	v_ashrrev_i32_e32 v2, 6, v2
	v_lshrrev_b32_e32 v8, 26, v8
	s_add_u32 s0, s4, s0
	v_lshlrev_b32_e32 v7, 3, v2
	v_add_u32_e32 v8, v6, v8
	s_addc_u32 s1, s5, s89
	v_and_b32_e32 v7, -16, v7
	v_ashrrev_i32_e32 v9, 6, v8
	v_and_b32_e32 v8, 0xc0, v8
	s_add_u32 s14, s0, 0x7aa0000
	v_add_u32_e32 v7, v9, v7
	v_sub_u32_e32 v6, v6, v8
	s_addc_u32 s15, s1, 0
	v_lshlrev_b32_e32 v2, 5, v2
	v_ashrrev_i16_sdwa v6, v1, sext(v6) dst_sel:DWORD dst_unused:UNUSED_PAD src0_sel:DWORD src1_sel:BYTE_0
	v_lshlrev_b32_e32 v8, 1, v7
	v_lshrrev_b32_e32 v10, 2, v7
	v_and_b32_e32 v9, 3, v9
	s_mov_b32 s1, 0xfffe0
	v_and_b32_e32 v2, 32, v2
	v_bfe_i32 v6, v6, 0, 16
	v_and_b32_e32 v8, 24, v8
	v_and_b32_e32 v10, 4, v10
	v_and_or_b32 v9, v7, s1, v9
	v_or3_b32 v8, v9, v10, v8
	v_add_lshl_u32 v6, v2, v6, 1
	v_add_u32_e32 v4, 0x2000, v4
	v_lshl_add_u32 v2, v7, 12, v6
	v_lshl_add_u32 v70, v8, 12, v6
	v_ashrrev_i32_e32 v6, 31, v4
	v_lshrrev_b32_e32 v6, 22, v6
	v_add_u32_e32 v6, v4, v6
	v_ashrrev_i32_e32 v6, 10, v6
	v_mul_i32_i24_e32 v7, 0x400, v6
	v_sub_u32_e32 v4, v4, v7
	v_lshrrev_b32_e32 v7, 4, v4
	v_bitop3_b32 v4, v7, v4, 32 bitop3:0x6c
	v_ashrrev_i32_e32 v8, 31, v4
	v_lshrrev_b32_e32 v8, 26, v8
	v_lshlrev_b32_e32 v7, 3, v6
	v_add_u32_e32 v8, v4, v8
	s_ashr_i32 s0, s22, 6
	v_and_b32_e32 v7, -16, v7
	v_ashrrev_i32_e32 v9, 6, v8
	v_and_b32_e32 v8, 0xc0, v8
	s_and_b32 s23, s0, 3
	v_add_u32_e32 v7, v9, v7
	v_sub_u32_e32 v4, v4, v8
	v_and_b32_e32 v9, 3, v9
	v_lshlrev_b32_e32 v6, 5, v6
	v_ashrrev_i16_sdwa v4, v1, sext(v4) dst_sel:DWORD dst_unused:UNUSED_PAD src0_sel:DWORD src1_sel:BYTE_0
	v_lshlrev_b32_e32 v8, 1, v7
	v_lshrrev_b32_e32 v10, 2, v7
	v_and_or_b32 v9, v7, s1, v9
	s_ashr_i32 s27, s22, 8
	s_lshl_b32 s1, s23, 14
	s_lshl_b32 s0, s0, 10
	s_lshl_b32 s24, s23, 10
	v_readlane_b32 s4, v254, 30
	v_and_b32_e32 v6, 32, v6
	v_bfe_i32 v4, v4, 0, 16
	v_and_b32_e32 v8, 24, v8
	v_and_b32_e32 v10, 4, v10
	v_readlane_b32 s5, v254, 31
	s_add_u32 s4, s14, s4
	v_or3_b32 v8, v9, v10, v8
	v_add_lshl_u32 v4, v6, v4, 1
	s_addc_u32 s5, s15, s5
	s_add_i32 s16, s0, 0
	v_lshl_add_u32 v71, v7, 12, v4
	v_lshl_add_u32 v72, v8, 12, v4
	v_and_b32_e32 v4, 15, v5
	v_bfe_u32 v5, v5, 4, 2
	s_add_i32 s17, s16, 0x10000
	s_mov_b32 s0, m0
	s_mov_b32 m0, s17
	s_nop 0
	global_load_lds_dwordx4 v70, s[4:5]
	s_mov_b32 m0, s0
	v_lshlrev_b32_e32 v6, 12, v5
	v_lshlrev_b32_e32 v7, 4, v4
	s_add_i32 s18, s16, 0x12000
	s_mov_b32 s0, m0
	s_mov_b32 m0, s18
	s_nop 0
	global_load_lds_dwordx4 v72, s[4:5]
	s_mov_b32 m0, s0
	v_or3_b32 v73, s1, v6, v7
	v_readlane_b32 s0, v254, 54
	v_readlane_b32 s1, v254, 55
	s_add_u32 s6, s12, s0
	s_addc_u32 s7, s13, s1
	s_add_u32 s0, s4, 0x80000
	s_addc_u32 s1, s5, 0
	s_add_i32 s19, s16, 0x14000
	s_mov_b32 s20, m0
	s_mov_b32 m0, s19
	s_nop 0
	global_load_lds_dwordx4 v70, s[0:1]
	s_mov_b32 m0, s20
	s_add_i32 s20, s16, 0x16000
	s_mov_b32 s21, m0
	s_mov_b32 m0, s20
	s_nop 0
	global_load_lds_dwordx4 v72, s[0:1]
	s_mov_b32 m0, s21
	s_mov_b32 s0, m0
	s_mov_b32 m0, s16
	s_nop 0
	global_load_lds_dwordx4 v2, s[6:7]
	s_mov_b32 m0, s0
	s_add_i32 s21, s16, 0x2000
	s_mov_b32 s0, m0
	s_mov_b32 m0, s21
	s_nop 0
	global_load_lds_dwordx4 v71, s[6:7]
	s_mov_b32 m0, s0
	s_add_u32 s0, s6, 0x100000
	s_addc_u32 s1, s7, 0
	s_add_i32 s24, s24, 0
	s_add_i32 s25, s24, 0x20400
	s_mov_b32 s28, m0
	s_mov_b32 m0, s25
	s_nop 0
	global_load_lds_dwordx4 v73, s[0:1]
	s_mov_b32 m0, s28
	s_add_u32 s0, s6, 0x80000
	s_addc_u32 s1, s7, 0
	s_add_i32 s25, s16, 0x4000
	s_mov_b32 s28, m0
	s_mov_b32 m0, s25
	s_nop 0
	global_load_lds_dwordx4 v2, s[0:1]
	s_mov_b32 m0, s28
	s_add_i32 s28, s16, 0x6000
	s_mov_b32 s29, m0
	s_mov_b32 m0, s28
	s_nop 0
	global_load_lds_dwordx4 v71, s[0:1]
	s_mov_b32 m0, s29
	s_cmp_eq_u32 s27, 1
	s_cselect_b64 s[0:1], -1, 0
	s_setprio 1
	s_cmp_lg_u32 s27, 1
	s_cbranch_scc1 .LBB0_1173
	s_setprio 0
	s_barrier

; #define PG8_STAGE(bufoff, gbase, voff) do { _Pragma("unroll") for (int _i = 0; _i < 2; ++_i) glds16_s((voff)[_i], (const void*)(gbase), ldsbase + (unsigned)((bufoff) + _i * 8192) + ldsw); } while (0)
; template <class Epi, class Sched, bool HM = false>
; __device__ __forceinline__ void gemm_phase(PG8_LAS unsigned char* lds, const Gemm g, const Sched& S, const Epi& E) {
;     ...
;     const int tid = tid_, wid = __builtin_amdgcn_readfirstlane(tid >> 6), lane = tid & 63, wr = wid >> 2, wc = wid & 3, fr = lane & 15, fq = lane >> 4;
;     const int K = g.K, nt = K / BK;
;     unsigned voffA[2], voffB[2];
; #pragma unroll
;     for (int i = 0; i < 2; ++i) { int R, C; stage_rc(tid * 16 + i * 8192, R, C); const int Rb = Epi::PERM ? ((R & ~31) + perm32(R & 31)) : R;
;         voffA[i] = (unsigned)(R * g.lda + C) * 2u; voffB[i] = (unsigned)(Rb * g.ldb + C) * 2u; }
;     const unsigned voffX = (unsigned)((4 * (wid & 3) + (lane >> 4)) * g.lda + 8 * (lane & 15)) * 2u;
;     const size_t kstep = (size_t)(BK * 2);
;     const size_t hstepA = (size_t)HALF * g.lda * 2, hstepB = (size_t)HALF * g.ldb * 2;
;     const size_t tstepA = (size_t)(HM ? HALF : g.pms) * g.lda * 2, tstepB = 2 * hstepB, xstep = 2 * hstepA; const bool hasx = g.pms != BM;
;     const unsigned ldsw = (unsigned)wid * 1024u, ldsx = (unsigned)(wid & 3) * 1024u;
;     const unsigned ldsbase = (unsigned)__builtin_amdgcn_readfirstlane((int)(unsigned)(__UINTPTR_TYPE__)lds);
;     const int aoff = lds_byte(wr * 64 + fr, fq * 8), boff = lds_byte(wc * 32 + fr, fq * 8);
;     const int xoff = XOFF + fr * 256 + fq * 16;
;     ...
;     Unit cur, nxt; int ui = 0;
;     if (!S.next(0, cur)) return;
;     f32x4 acc[2][2][4][2]; f32x4 accx[2];
; #pragma unroll
;     for (int a = 0; a < 2; ++a)
; #pragma unroll
;         for (int b = 0; b < 2; ++b)
; #pragma unroll
;             for (int m = 0; m < 4; ++m)
; #pragma unroll
;                 for (int n = 0; n < 2; ++n) acc[a][b][m][n] = (f32x4){0.f, 0.f, 0.f, 0.f};
;     accx[0] = (f32x4){0.f, 0.f, 0.f, 0.f}; accx[1] = accx[0];
;     bf16x8 At[4][2], B0[2][2], B1[2][2], Ax[2];
;     const char* cA = PG8_APTR(cur); const char* cB = PG8_BPTR(cur);
;     S.a_ready(cur);
;     PG8_STAGE(PG8_SB(0, 0), cB, voffB); PG8_STAGE(PG8_SB(0, 1), cB + hstepB, voffB); PG8_STAGE(PG8_SA(0, 0), cA, voffA); PG8_STAGEX(0, cA + xstep); PG8_STAGE(PG8_SA(0, 1), cA + hstepA, voffA);
;     if (wr == 1) PG8_BAR;
.LBB0_1250:
	s_mov_b64 s[4:5], s[30:31]
	s_mov_b64 s[0:1], s[30:31]
	s_mov_b64 s[8:9], s[30:31]
	v_mov_b32_e32 v4, v0
	s_andn2_b64 vcc, exec, s[96:97]
	v_readfirstlane_b32 s20, v4
	s_cbranch_vccnz .LBB0_1249
	v_bfe_i32 v7, v4, 27, 1
	v_lshlrev_b32_e32 v5, 4, v4
	v_lshrrev_b32_e32 v7, 22, v7
	v_add_u32_e32 v7, v5, v7
	v_and_b32_e32 v7, 0xfffffc00, v7
	v_sub_u32_e32 v7, v5, v7
	v_lshrrev_b32_e32 v8, 4, v7
	v_ashrrev_i32_e32 v6, 31, v4
	v_bitop3_b32 v7, v8, v7, 32 bitop3:0x6c
	s_add_u32 s13, s4, 0x30084000
	v_lshrrev_b32_e32 v6, 26, v6
	v_ashrrev_i32_e32 v9, 31, v7
	s_addc_u32 s14, s5, 0
	v_readlane_b32 s5, v255, 17
	v_add_u32_e32 v6, v4, v6
	v_lshrrev_b32_e32 v9, 26, v9
	s_mul_i32 s4, s5, 0x1600000
	v_ashrrev_i32_e32 v6, 6, v6
	v_add_u32_e32 v9, v7, v9
	s_add_u32 s0, s0, s4
	s_mul_hi_u32 s4, s5, 0x1600000
	v_lshlrev_b32_e32 v8, 3, v6
	v_ashrrev_i32_e32 v10, 6, v9
	v_and_b32_e32 v9, 0xc0, v9
	s_addc_u32 s1, s1, s4
	v_and_b32_e32 v8, -16, v8
	v_lshlrev_b32_e32 v6, 5, v6
	v_sub_u32_e32 v7, v7, v9
	s_add_u32 s15, s0, 0x102a0000
	v_add_u32_e32 v8, v10, v8
	v_and_b32_e32 v6, 32, v6
	v_ashrrev_i16_sdwa v7, v1, sext(v7) dst_sel:DWORD dst_unused:UNUSED_PAD src0_sel:DWORD src1_sel:BYTE_0
	s_addc_u32 s16, s1, 0
	v_add_u32_sdwa v6, v6, sext(v7) dst_sel:DWORD dst_unused:UNUSED_PAD src0_sel:DWORD src1_sel:WORD_0
	v_lshlrev_b32_e32 v7, 1, v8
	v_lshrrev_b32_e32 v9, 2, v8
	v_and_b32_e32 v10, 3, v10
	s_mov_b32 s1, 0x7fffe0
	v_and_b32_e32 v7, 24, v7
	v_and_b32_e32 v9, 4, v9
	v_and_or_b32 v10, v8, s1, v10
	v_or3_b32 v7, v10, v9, v7
	s_movk_i32 s4, 0x1600
	v_mul_lo_u32 v8, v8, s4
	v_mul_u32_u24_e32 v7, 0x1600, v7
	v_add_u32_e32 v5, 0x2000, v5
	v_add_lshl_u32 v225, v6, v8, 1
	v_add_lshl_u32 v226, v7, v6, 1
	v_ashrrev_i32_e32 v6, 31, v5
	v_lshrrev_b32_e32 v6, 22, v6
	v_add_u32_e32 v6, v5, v6
	v_ashrrev_i32_e32 v6, 10, v6
	v_mul_i32_i24_e32 v7, 0x400, v6
	v_sub_u32_e32 v5, v5, v7
	v_lshrrev_b32_e32 v7, 4, v5
	v_bitop3_b32 v5, v7, v5, 32 bitop3:0x6c
	v_ashrrev_i32_e32 v8, 31, v5
	v_lshrrev_b32_e32 v8, 26, v8
	v_add_u32_e32 v8, v5, v8
	v_lshlrev_b32_e32 v7, 3, v6
	v_ashrrev_i32_e32 v9, 6, v8
	v_and_b32_e32 v8, 0xc0, v8
	s_ashr_i32 s0, s20, 6
	v_and_b32_e32 v7, -16, v7
	v_lshlrev_b32_e32 v6, 5, v6
	v_sub_u32_e32 v5, v5, v8
	s_and_b32 s21, s0, 3
	v_add_u32_e32 v7, v9, v7
	v_and_b32_e32 v6, 32, v6
	v_ashrrev_i16_sdwa v5, v1, sext(v5) dst_sel:DWORD dst_unused:UNUSED_PAD src0_sel:DWORD src1_sel:BYTE_0
	v_and_b32_e32 v9, 3, v9
	v_add_u32_sdwa v5, v6, sext(v5) dst_sel:DWORD dst_unused:UNUSED_PAD src0_sel:DWORD src1_sel:WORD_0
	v_lshlrev_b32_e32 v6, 1, v7
	v_lshrrev_b32_e32 v8, 2, v7
	v_and_or_b32 v9, v7, s1, v9
	s_ashr_i32 s22, s20, 8
	s_lshl_b32 s0, s0, 10
	s_lshl_b32 s23, s21, 10
	v_readlane_b32 s1, v254, 50
	v_and_b32_e32 v6, 24, v6
	v_and_b32_e32 v8, 4, v8
	v_mul_lo_u32 v7, v7, s4
	s_add_u32 s4, s15, s1
	v_readlane_b32 s1, v254, 51
	v_or3_b32 v6, v9, v8, v6
	s_addc_u32 s5, s16, s1
	s_add_i32 s17, s0, 0
	v_mul_u32_u24_e32 v6, 0x1600, v6
	s_add_i32 s18, s17, 0x10000
	s_mov_b32 s0, m0
	s_mov_b32 m0, s18
	s_nop 0
	global_load_lds_dwordx4 v226, s[4:5]
	s_mov_b32 m0, s0
	v_add_lshl_u32 v228, v6, v5, 1
	s_add_i32 s19, s17, 0x12000
	s_mov_b32 s0, m0
	s_mov_b32 m0, s19
	s_nop 0
	global_load_lds_dwordx4 v228, s[4:5]
	s_mov_b32 m0, s0
	v_readlane_b32 s1, v254, 23
	s_mul_i32 s0, s1, s10
	s_add_u32 s6, s13, s0
	s_mul_hi_i32 s0, s1, s10
	s_addc_u32 s7, s14, s0
	s_add_u32 s0, s4, 0x160000
	s_addc_u32 s1, s5, 0
	s_add_i32 s24, s17, 0x14000
	s_mov_b32 s25, m0
	s_mov_b32 m0, s24
	s_nop 0
	global_load_lds_dwordx4 v226, s[0:1]
	s_mov_b32 m0, s25
	s_add_i32 s25, s17, 0x16000
	s_mov_b32 s27, m0
	s_mov_b32 m0, s25
	s_nop 0
	global_load_lds_dwordx4 v228, s[0:1]
	s_mov_b32 m0, s27
	v_readlane_b32 s0, v254, 37
	s_add_u32 s6, s6, s0
	v_readlane_b32 s0, v254, 36
	s_addc_u32 s7, s7, s0
	s_mov_b32 s0, m0
	s_mov_b32 m0, s17
	s_nop 0
	global_load_lds_dwordx4 v225, s[6:7]
	s_mov_b32 m0, s0
	v_add_lshl_u32 v227, v5, v7, 1
	s_add_i32 s28, s17, 0x2000
	s_mov_b32 s0, m0
	s_mov_b32 m0, s28
	s_nop 0
	global_load_lds_dwordx4 v227, s[6:7]
	s_mov_b32 m0, s0
	v_bfe_u32 v2, v4, 4, 2
	s_add_u32 s0, s6, 0x2c0000
	v_lshl_or_b32 v5, s21, 2, v2
	v_lshlrev_b32_e32 v232, 4, v5
	s_addc_u32 s1, s7, 0
	s_add_i32 s29, s23, 0
	v_and_b32_e32 v4, 15, v4
	v_mul_u32_u24_e32 v5, 0x2c00, v5
	s_add_i32 s23, s29, 0x20400
	v_lshl_or_b32 v229, v4, 4, v5
	v_xor_b32_e32 v229, v229, v232
	s_mov_b32 s27, m0
	s_mov_b32 m0, s23
	s_nop 0
	global_load_lds_dwordx4 v229, s[0:1]
	s_mov_b32 m0, s27
	s_add_u32 s0, s6, 0x160000
	s_addc_u32 s1, s7, 0
	s_add_i32 s30, s17, 0x4000
	s_mov_b32 s23, m0
	s_mov_b32 m0, s30
	s_nop 0
	global_load_lds_dwordx4 v225, s[0:1]
	s_mov_b32 m0, s23
	s_add_i32 s31, s17, 0x6000
	s_mov_b32 s23, m0
	s_mov_b32 m0, s31
	s_nop 0
	global_load_lds_dwordx4 v227, s[0:1]
	s_mov_b32 m0, s23
	s_cmp_eq_u32 s22, 1
	s_cselect_b64 s[0:1], -1, 0
	s_setprio 1
	s_cmp_lg_u32 s22, 1
	s_cbranch_scc1 .LBB0_1253
	s_setprio 0
	s_barrier
